# down GEMM: each workgroup touches its residual tile (one dword per 128-B line) mid K-loop so the epilogue's f32 reads hit cache instead of joining the HBM burst; long nops trimmed in attention
# baseline (speedup 1.0000x reference)
; #define PG8_STAGE(bufoff, gbase, voff) do { _Pragma("unroll") for (int _i = 0; _i < 2; ++_i) \
;         __builtin_amdgcn_global_load_lds((const unsigned*)((const char*)(gbase) + (voff)[_i]), (PG8_LAS unsigned*)(lds + (bufoff) + ldsw + _i * 8192), 16, 0, 0); } while (0)
; #define PG8_LDA(dst, b, h) do { _Pragma("unroll") for (int m = 0; m < 4; ++m) _Pragma("unroll") for (int k = 0; k < 2; ++k) dst[m][k] = *(const PG8_LAS bf16x8*)(lds + PG8_SA(b, h) + aoff + m * 2048 + k * 1024); } while (0)
; #define PG8_LDB(dst, b, h) do { _Pragma("unroll") for (int n = 0; n < 2; ++n) _Pragma("unroll") for (int k = 0; k < 2; ++k) dst[n][k] = *(const PG8_LAS bf16x8*)(lds + PG8_SB(b, h) + boff + n * 2048 + k * 1024); } while (0)
; #define PG8_BAR __builtin_amdgcn_s_barrier()
; template <class Epi, class Sched, bool ALIGN_EPI = false, bool SP2 = false>
; __device__ __forceinline__ void gemm_phase(PG8_LAS unsigned char* lds, const Gemm g, const Sched& S, const Epi& E, const int wave0) {
;     ...
;         for (int t = 0; t < nt; t += 2) {
;             const bool last = (t == nt - 2);
;             const char* a1 = cA + (size_t)(t + 1) * kstep;
;             const char* a2 = last ? nA : cA + (size_t)(t + 2) * kstep; const char* b2 = last ? nB : cB + (size_t)(t + 2) * kstep;
;             const char* a3 = a2 + kstep; const char* b3 = b2 + kstep;
;             if (last && has_next) S.a_ready(nxt);
;             if constexpr (SP2) {
;             PG8_LDB(B0, 0, 0); PG8_LDB(B1, 0, 1); PG8_SCHED; PG8_LDA(At, 0, 0); PG8_STAGE(PG8_SA(1, 1), a1 + hstep, voffA);
;             PG8_WAIT_V(8); PG8_WAIT_L(0); PG8_BAR; PG8_MMA(0, 0, At, B0); PG8_MMA(0, 1, At, B1); PG8_BAR; PG8_SCHED;
;             PG8_LDA(At, 0, 1); PG8_STAGE(PG8_SB(0, 0), b2, voffB); PG8_STAGE(PG8_SB(0, 1), b2 + hstep, voffB); PG8_STAGE(PG8_SA(0, 0), a2, voffA);
;             PG8_WAIT_V(8); PG8_WAIT_L(0); PG8_BAR; PG8_MMA(1, 0, At, B0); PG8_MMA(1, 1, At, B1); PG8_BAR; PG8_SCHED;
;     __device__ __forceinline__ void operator()(const pg8::f32x4 (&acc)[2][2][4][2], const pg8::Unit& u, int wr, int wc, int fr, int fq) const {
;     ...
;                     const size_t ro = (size_t)(rowb + 128 * ai + 16 * m) * ldc + colb;
; #pragma unroll
;                     for (int bj = 0; bj < 2; ++bj)
; #pragma unroll
;                         for (int n = 0; n < 2; ++n) pre[m][bj][n] = *(const pg8::f32x4*)(fin + ro + 128 * bj + NS * n);
.LBB0_1024:
	s_add_u32 s8, s10, 0x100
	s_addc_u32 s9, s11, 0
	s_add_i32 s18, 0, 0x10000
	s_cmp_eq_u32 s59, 40
	s_cselect_b32 s51, s45, s9
	s_cselect_b32 s50, s44, s8
	s_cselect_b32 s49, s47, s58
	s_cselect_b32 s48, s46, s57
	s_cmp_lg_u32 s59, 6
	s_cbranch_scc1 .Lpf2816_a
	global_load_dwordx2 v[240:241], v215, s[40:41] offset:1048
.Lpf2816_a:
	s_cmp_lg_u32 s59, 14
	s_cbranch_scc1 .Lpf2816_b
	v_lshrrev_b32_e32 v242, 1, v246
	v_lshl_add_u32 v242, s56, 8, v242
	v_lshlrev_b32_e32 v242, 12, v242
	v_and_b32_e32 v243, 1, v246
	v_lshlrev_b32_e32 v243, 9, v243
	v_lshl_add_u32 v243, s55, 10, v243
	v_add_u32_e32 v242, v242, v243
	v_mov_b32_e32 v243, 0
	v_lshl_add_u64 v[242:243], v[242:243], 0, v[240:241]
	global_load_dword v238, v[242:243], off
	global_load_dword v238, v[242:243], off offset:128
	global_load_dword v238, v[242:243], off offset:256
	global_load_dword v238, v[242:243], off offset:384
.Lpf2816_b:
	s_add_i32 s19, 0, 0x14000
	v_add_u32_e32 v140, s18, v247
	v_add_u32_e32 v156, s19, v247
	ds_read_b128 v[64:67], v140
	ds_read_b128 v[68:71], v140 offset:1024
	ds_read_b128 v[136:139], v140 offset:2048
	ds_read_b128 v[140:143], v140 offset:3072
	ds_read_b128 v[144:147], v156
	ds_read_b128 v[148:151], v156 offset:1024
	ds_read_b128 v[152:155], v156 offset:2048
	ds_read_b128 v[156:159], v156 offset:3072
	s_add_i32 m0, s33, 0xc000
	ds_read_b128 v[160:163], v245
	ds_read_b128 v[164:167], v245 offset:1024
	ds_read_b128 v[168:171], v245 offset:2048
	ds_read_b128 v[172:175], v245 offset:3072
	ds_read_b128 v[176:179], v245 offset:4096
	ds_read_b128 v[180:183], v245 offset:5120
	ds_read_b128 v[184:187], v245 offset:6144
	ds_read_b128 v[188:191], v245 offset:7168
	global_load_lds_dwordx4 v224, s[10:11]
	s_add_i32 m0, s33, 0xe000
	s_nop 0
	global_load_lds_dwordx4 v226, s[10:11]
	s_waitcnt vmcnt(8)
	s_waitcnt lgkmcnt(0)
	s_barrier
	s_setprio 1
	s_waitcnt lgkmcnt(0)
	v_mfma_f32_16x16x32_bf16 v[132:135], v[64:67], v[160:163], v[132:135]
	v_mfma_f32_16x16x32_bf16 v[128:131], v[136:139], v[160:163], v[128:131]
	v_mfma_f32_16x16x32_bf16 v[116:119], v[64:67], v[168:171], v[116:119]
	v_mfma_f32_16x16x32_bf16 v[108:111], v[136:139], v[168:171], v[108:111]
	v_mfma_f32_16x16x32_bf16 v[100:103], v[64:67], v[176:179], v[100:103]
	v_mfma_f32_16x16x32_bf16 v[92:95], v[136:139], v[176:179], v[92:95]
	v_mfma_f32_16x16x32_bf16 v[84:87], v[64:67], v[184:187], v[84:87]
	v_mfma_f32_16x16x32_bf16 v[76:79], v[136:139], v[184:187], v[76:79]
	v_mfma_f32_16x16x32_bf16 v[132:135], v[68:71], v[164:167], v[132:135]
	v_mfma_f32_16x16x32_bf16 v[128:131], v[140:143], v[164:167], v[128:131]
	v_mfma_f32_16x16x32_bf16 v[116:119], v[68:71], v[172:175], v[116:119]
	v_mfma_f32_16x16x32_bf16 v[108:111], v[140:143], v[172:175], v[108:111]
	v_mfma_f32_16x16x32_bf16 v[100:103], v[68:71], v[180:183], v[100:103]
	v_mfma_f32_16x16x32_bf16 v[92:95], v[140:143], v[180:183], v[92:95]
	v_mfma_f32_16x16x32_bf16 v[84:87], v[68:71], v[188:191], v[84:87]
	v_mfma_f32_16x16x32_bf16 v[76:79], v[140:143], v[188:191], v[76:79]
	s_setprio 0
	s_setprio 1
	v_mfma_f32_16x16x32_bf16 v[124:127], v[144:147], v[160:163], v[124:127]
	v_mfma_f32_16x16x32_bf16 v[120:123], v[152:155], v[160:163], v[120:123]
	v_mfma_f32_16x16x32_bf16 v[112:115], v[144:147], v[168:171], v[112:115]
	v_mfma_f32_16x16x32_bf16 v[104:107], v[152:155], v[168:171], v[104:107]
	v_mfma_f32_16x16x32_bf16 v[96:99], v[144:147], v[176:179], v[96:99]
	v_mfma_f32_16x16x32_bf16 v[88:91], v[152:155], v[176:179], v[88:91]
	v_mfma_f32_16x16x32_bf16 v[80:83], v[144:147], v[184:187], v[80:83]
	v_mfma_f32_16x16x32_bf16 v[72:75], v[152:155], v[184:187], v[72:75]
	v_mfma_f32_16x16x32_bf16 v[124:127], v[148:151], v[164:167], v[124:127]
	v_mfma_f32_16x16x32_bf16 v[120:123], v[156:159], v[164:167], v[120:123]
	v_mfma_f32_16x16x32_bf16 v[112:115], v[148:151], v[172:175], v[112:115]
	v_mfma_f32_16x16x32_bf16 v[104:107], v[156:159], v[172:175], v[104:107]
	v_mfma_f32_16x16x32_bf16 v[96:99], v[148:151], v[180:183], v[96:99]
	v_mfma_f32_16x16x32_bf16 v[88:91], v[156:159], v[180:183], v[88:91]
	v_mfma_f32_16x16x32_bf16 v[80:83], v[148:151], v[188:191], v[80:83]
	v_mfma_f32_16x16x32_bf16 v[72:75], v[156:159], v[188:191], v[72:75]
	s_setprio 0
	s_barrier
	s_add_i32 s10, s18, s95
	s_mov_b32 m0, s10
	ds_read_b128 v[160:163], v245 offset:16384
	ds_read_b128 v[164:167], v245 offset:17408
	ds_read_b128 v[168:171], v245 offset:18432
	ds_read_b128 v[172:175], v245 offset:19456
	ds_read_b128 v[176:179], v245 offset:20480
	ds_read_b128 v[180:183], v245 offset:21504
	ds_read_b128 v[184:187], v245 offset:22528
	ds_read_b128 v[188:191], v245 offset:23552
	global_load_lds_dwordx4 v218, s[48:49]
	s_add_i32 m0, s10, 0x2000
	s_add_u32 s10, s48, 0xb0000
	s_addc_u32 s11, s49, 0
	s_add_i32 s18, s19, s95
	global_load_lds_dwordx4 v222, s[48:49]
	s_mov_b32 m0, s18
	s_nop 0
	global_load_lds_dwordx4 v218, s[10:11]
	s_add_i32 m0, s18, 0x2000
	s_nop 0
	global_load_lds_dwordx4 v222, s[10:11]
	s_mov_b32 m0, s33
	s_nop 0
	global_load_lds_dwordx4 v216, s[50:51]
	s_mov_b32 m0, s82
	s_nop 0
	global_load_lds_dwordx4 v220, s[50:51]
	s_waitcnt vmcnt(8)
	s_waitcnt lgkmcnt(0)
	s_barrier
; #define PG8_STAGE(bufoff, gbase, voff) do { _Pragma("unroll") for (int _i = 0; _i < 2; ++_i) \
;         __builtin_amdgcn_global_load_lds((const unsigned*)((const char*)(gbase) + (voff)[_i]), (PG8_LAS unsigned*)(lds + (bufoff) + ldsw + _i * 8192), 16, 0, 0); } while (0)
; #define PG8_LDA(dst, b, h) do { _Pragma("unroll") for (int m = 0; m < 4; ++m) _Pragma("unroll") for (int k = 0; k < 2; ++k) dst[m][k] = *(const PG8_LAS bf16x8*)(lds + PG8_SA(b, h) + aoff + m * 2048 + k * 1024); } while (0)
; #define PG8_LDB(dst, b, h) do { _Pragma("unroll") for (int n = 0; n < 2; ++n) _Pragma("unroll") for (int k = 0; k < 2; ++k) dst[n][k] = *(const PG8_LAS bf16x8*)(lds + PG8_SB(b, h) + boff + n * 2048 + k * 1024); } while (0)
; #define PG8_MMA(ai, bj, At, Bt) do { __builtin_amdgcn_s_setprio(1); _Pragma("unroll") for (int m = 0; m < 4; ++m) _Pragma("unroll") for (int n = 0; n < 2; ++n) _Pragma("unroll") for (int k = 0; k < 2; ++k) \
;         acc[ai][bj][m][n] = __builtin_amdgcn_mfma_f32_16x16x32_bf16(Bt[n][k], At[m][k], acc[ai][bj][m][n], 0, 0, 0); __builtin_amdgcn_s_setprio(0); } while (0)
; #define PG8_WAIT_V(n) asm volatile("s_waitcnt vmcnt(" #n ")" ::: "memory")
; #define PG8_WAIT_L(n) asm volatile("s_waitcnt lgkmcnt(" #n ")" ::: "memory")
; #define PG8_BAR __builtin_amdgcn_s_barrier()
; #define PG8_SCHED __builtin_amdgcn_sched_barrier(0)
; template <class Epi, class Sched, bool ALIGN_EPI = false, bool SP2 = false>
; __device__ __forceinline__ void gemm_phase(PG8_LAS unsigned char* lds, const Gemm g, const Sched& S, const Epi& E, const int wave0) {
;     ...
;             PG8_WAIT_V(8); PG8_WAIT_L(0); PG8_BAR; PG8_MMA(1, 0, At, B0); PG8_MMA(1, 1, At, B1); PG8_BAR; PG8_SCHED;
;             PG8_LDB(B0, 1, 0); PG8_LDB(B1, 1, 1); PG8_SCHED; PG8_LDA(At, 1, 0); PG8_STAGE(PG8_SA(0, 1), a2 + hstep, voffA);
;             PG8_WAIT_V(8); PG8_WAIT_L(0); PG8_BAR; PG8_MMA(0, 0, At, B0); PG8_MMA(0, 1, At, B1); PG8_BAR; PG8_SCHED;
	s_setprio 1
	s_waitcnt lgkmcnt(0)
	v_mfma_f32_16x16x32_bf16 v[60:63], v[64:67], v[160:163], v[60:63]
	v_mfma_f32_16x16x32_bf16 v[52:55], v[136:139], v[160:163], v[52:55]
	v_mfma_f32_16x16x32_bf16 v[44:47], v[64:67], v[168:171], v[44:47]
	v_mfma_f32_16x16x32_bf16 v[36:39], v[136:139], v[168:171], v[36:39]
	v_mfma_f32_16x16x32_bf16 v[28:31], v[64:67], v[176:179], v[28:31]
	v_mfma_f32_16x16x32_bf16 v[20:23], v[136:139], v[176:179], v[20:23]
	v_mfma_f32_16x16x32_bf16 v[12:15], v[64:67], v[184:187], v[12:15]
	v_mfma_f32_16x16x32_bf16 v[4:7], v[136:139], v[184:187], v[4:7]
	v_mfma_f32_16x16x32_bf16 v[60:63], v[68:71], v[164:167], v[60:63]
	v_mfma_f32_16x16x32_bf16 v[52:55], v[140:143], v[164:167], v[52:55]
	v_mfma_f32_16x16x32_bf16 v[44:47], v[68:71], v[172:175], v[44:47]
	v_mfma_f32_16x16x32_bf16 v[36:39], v[140:143], v[172:175], v[36:39]
	v_mfma_f32_16x16x32_bf16 v[28:31], v[68:71], v[180:183], v[28:31]
	v_mfma_f32_16x16x32_bf16 v[20:23], v[140:143], v[180:183], v[20:23]
	v_mfma_f32_16x16x32_bf16 v[12:15], v[68:71], v[188:191], v[12:15]
	v_mfma_f32_16x16x32_bf16 v[4:7], v[140:143], v[188:191], v[4:7]
	s_setprio 0
	s_setprio 1
	v_mfma_f32_16x16x32_bf16 v[56:59], v[144:147], v[160:163], v[56:59]
	v_mfma_f32_16x16x32_bf16 v[48:51], v[152:155], v[160:163], v[48:51]
	v_mfma_f32_16x16x32_bf16 v[40:43], v[144:147], v[168:171], v[40:43]
	v_mfma_f32_16x16x32_bf16 v[32:35], v[152:155], v[168:171], v[32:35]
	v_mfma_f32_16x16x32_bf16 v[24:27], v[144:147], v[176:179], v[24:27]
	v_mfma_f32_16x16x32_bf16 v[16:19], v[152:155], v[176:179], v[16:19]
	v_mfma_f32_16x16x32_bf16 v[8:11], v[144:147], v[184:187], v[8:11]
	v_mfma_f32_16x16x32_bf16 v[0:3], v[152:155], v[184:187], v[0:3]
	v_mfma_f32_16x16x32_bf16 v[56:59], v[148:151], v[164:167], v[56:59]
	v_mfma_f32_16x16x32_bf16 v[48:51], v[156:159], v[164:167], v[48:51]
	v_mfma_f32_16x16x32_bf16 v[40:43], v[148:151], v[172:175], v[40:43]
	v_mfma_f32_16x16x32_bf16 v[32:35], v[156:159], v[172:175], v[32:35]
	v_mfma_f32_16x16x32_bf16 v[24:27], v[148:151], v[180:183], v[24:27]
	v_mfma_f32_16x16x32_bf16 v[16:19], v[156:159], v[180:183], v[16:19]
	v_mfma_f32_16x16x32_bf16 v[8:11], v[148:151], v[188:191], v[8:11]
	v_mfma_f32_16x16x32_bf16 v[0:3], v[156:159], v[188:191], v[0:3]
	s_setprio 0
	s_barrier
	s_add_i32 s18, 0, 0x18000
	s_add_i32 s19, 0, 0x1c000
	v_add_u32_e32 v140, s18, v247
	v_add_u32_e32 v156, s19, v247
	ds_read_b128 v[64:67], v140
	ds_read_b128 v[68:71], v140 offset:1024
	ds_read_b128 v[136:139], v140 offset:2048
	ds_read_b128 v[140:143], v140 offset:3072
	ds_read_b128 v[144:147], v156
	ds_read_b128 v[148:151], v156 offset:1024
	ds_read_b128 v[152:155], v156 offset:2048
	ds_read_b128 v[156:159], v156 offset:3072
	s_add_u32 s10, s50, 0xb0000
	s_addc_u32 s11, s51, 0
	s_mov_b32 m0, s16
	ds_read_b128 v[160:163], v245 offset:32768
	ds_read_b128 v[164:167], v245 offset:33792
	ds_read_b128 v[168:171], v245 offset:34816
	ds_read_b128 v[172:175], v245 offset:35840
	ds_read_b128 v[176:179], v245 offset:36864
	ds_read_b128 v[180:183], v245 offset:37888
	ds_read_b128 v[184:187], v245 offset:38912
	ds_read_b128 v[188:191], v245 offset:39936
	global_load_lds_dwordx4 v216, s[10:11]
	s_mov_b32 m0, s83
	s_nop 0
	global_load_lds_dwordx4 v220, s[10:11]
	s_waitcnt vmcnt(8)
	s_waitcnt lgkmcnt(0)
	s_barrier
	s_setprio 1
	s_waitcnt lgkmcnt(0)
	v_mfma_f32_16x16x32_bf16 v[132:135], v[64:67], v[160:163], v[132:135]
	v_mfma_f32_16x16x32_bf16 v[128:131], v[136:139], v[160:163], v[128:131]
	v_mfma_f32_16x16x32_bf16 v[116:119], v[64:67], v[168:171], v[116:119]
	v_mfma_f32_16x16x32_bf16 v[108:111], v[136:139], v[168:171], v[108:111]
	v_mfma_f32_16x16x32_bf16 v[100:103], v[64:67], v[176:179], v[100:103]
	v_mfma_f32_16x16x32_bf16 v[92:95], v[136:139], v[176:179], v[92:95]
	v_mfma_f32_16x16x32_bf16 v[84:87], v[64:67], v[184:187], v[84:87]
	v_mfma_f32_16x16x32_bf16 v[76:79], v[136:139], v[184:187], v[76:79]
	v_mfma_f32_16x16x32_bf16 v[132:135], v[68:71], v[164:167], v[132:135]
	v_mfma_f32_16x16x32_bf16 v[128:131], v[140:143], v[164:167], v[128:131]
	v_mfma_f32_16x16x32_bf16 v[116:119], v[68:71], v[172:175], v[116:119]
	v_mfma_f32_16x16x32_bf16 v[108:111], v[140:143], v[172:175], v[108:111]
	v_mfma_f32_16x16x32_bf16 v[100:103], v[68:71], v[180:183], v[100:103]
	v_mfma_f32_16x16x32_bf16 v[92:95], v[140:143], v[180:183], v[92:95]
	v_mfma_f32_16x16x32_bf16 v[84:87], v[68:71], v[188:191], v[84:87]
	v_mfma_f32_16x16x32_bf16 v[76:79], v[140:143], v[188:191], v[76:79]
	s_setprio 0
	s_setprio 1
	v_mfma_f32_16x16x32_bf16 v[124:127], v[144:147], v[160:163], v[124:127]
	v_mfma_f32_16x16x32_bf16 v[120:123], v[152:155], v[160:163], v[120:123]
	v_mfma_f32_16x16x32_bf16 v[112:115], v[144:147], v[168:171], v[112:115]
	v_mfma_f32_16x16x32_bf16 v[104:107], v[152:155], v[168:171], v[104:107]
	v_mfma_f32_16x16x32_bf16 v[96:99], v[144:147], v[176:179], v[96:99]
	v_mfma_f32_16x16x32_bf16 v[88:91], v[152:155], v[176:179], v[88:91]
	v_mfma_f32_16x16x32_bf16 v[80:83], v[144:147], v[184:187], v[80:83]
	v_mfma_f32_16x16x32_bf16 v[72:75], v[152:155], v[184:187], v[72:75]
	v_mfma_f32_16x16x32_bf16 v[124:127], v[148:151], v[164:167], v[124:127]
	v_mfma_f32_16x16x32_bf16 v[120:123], v[156:159], v[164:167], v[120:123]
	v_mfma_f32_16x16x32_bf16 v[112:115], v[148:151], v[172:175], v[112:115]
	v_mfma_f32_16x16x32_bf16 v[104:107], v[156:159], v[172:175], v[104:107]
	v_mfma_f32_16x16x32_bf16 v[96:99], v[148:151], v[180:183], v[96:99]
	v_mfma_f32_16x16x32_bf16 v[88:91], v[156:159], v[180:183], v[88:91]
	v_mfma_f32_16x16x32_bf16 v[80:83], v[148:151], v[188:191], v[80:83]
	v_mfma_f32_16x16x32_bf16 v[72:75], v[156:159], v[188:191], v[72:75]
	s_setprio 0
	s_barrier
; #define PG8_STAGE(bufoff, gbase, voff) do { _Pragma("unroll") for (int _i = 0; _i < 2; ++_i) \
;         __builtin_amdgcn_global_load_lds((const unsigned*)((const char*)(gbase) + (voff)[_i]), (PG8_LAS unsigned*)(lds + (bufoff) + ldsw + _i * 8192), 16, 0, 0); } while (0)
; #define PG8_LDA(dst, b, h) do { _Pragma("unroll") for (int m = 0; m < 4; ++m) _Pragma("unroll") for (int k = 0; k < 2; ++k) dst[m][k] = *(const PG8_LAS bf16x8*)(lds + PG8_SA(b, h) + aoff + m * 2048 + k * 1024); } while (0)
; #define PG8_BAR __builtin_amdgcn_s_barrier()
; template <class Epi, class Sched, bool ALIGN_EPI = false, bool SP2 = false>
; __device__ __forceinline__ void gemm_phase(PG8_LAS unsigned char* lds, const Gemm g, const Sched& S, const Epi& E, const int wave0) {
;     ...
;             PG8_LDA(At, 1, 1); PG8_STAGE(PG8_SB(1, 0), b3, voffB); PG8_STAGE(PG8_SB(1, 1), b3 + hstep, voffB); PG8_STAGE(PG8_SA(1, 0), a3, voffA);
;             PG8_WAIT_V(8); PG8_WAIT_L(0); PG8_BAR; PG8_MMA(1, 0, At, B0); PG8_MMA(1, 1, At, B1); PG8_BAR; PG8_SCHED;
;             } else {
;             PG8_LDB(B0, 0, 0); PG8_SCHED; PG8_LDA(At, 0, 0); PG8_STAGE(PG8_SA(1, 1), a1 + hstep, voffA);
;             PG8_WAIT_L(8); PG8_BAR; PG8_WAIT_L(0); PG8_MMA(0, 0, At, B0); PG8_BAR; PG8_SCHED;
;             PG8_LDB(B1, 0, 1); PG8_STAGE(PG8_SB(0, 0), b2, voffB);
;             PG8_BAR; PG8_WAIT_L(0); PG8_MMA(0, 1, At, B1); PG8_BAR;
;             PG8_LDA(At, 0, 1); PG8_STAGE(PG8_SA(0, 0), a2, voffA);
;             PG8_BAR; PG8_WAIT_L(0); PG8_MMA(1, 0, At, B0); PG8_BAR; PG8_SCHED;
;             PG8_STAGE(PG8_SB(0, 1), b2 + hstep, voffB);
;             PG8_WAIT_V(6); PG8_BAR; PG8_MMA(1, 1, At, B1); PG8_BAR;
;             PG8_LDB(B0, 1, 0); PG8_SCHED; PG8_LDA(At, 1, 0); PG8_STAGE(PG8_SA(0, 1), a2 + hstep, voffA);
;             PG8_WAIT_L(8); PG8_BAR; PG8_WAIT_L(0); PG8_MMA(0, 0, At, B0); PG8_BAR; PG8_SCHED;
;             PG8_LDB(B1, 1, 1); PG8_STAGE(PG8_SB(1, 0), b3, voffB);
;             PG8_BAR; PG8_WAIT_L(0); PG8_MMA(0, 1, At, B1); PG8_BAR;
;             PG8_LDA(At, 1, 1); PG8_STAGE(PG8_SA(1, 0), a3, voffA);
;             PG8_BAR; PG8_WAIT_L(0); PG8_MMA(1, 0, At, B0); PG8_BAR; PG8_SCHED;
;             PG8_STAGE(PG8_SB(1, 1), b3 + hstep, voffB);
;             PG8_WAIT_V(6); PG8_BAR; PG8_MMA(1, 1, At, B1); PG8_BAR;
;             }
;         }
;         if constexpr (ALIGN_EPI) { if (wr == 0) PG8_BAR; }
	s_add_i32 s10, s18, s95
	s_add_i32 m0, s10, 0xffffff80
	ds_read_b128 v[160:163], v245 offset:49152
	ds_read_b128 v[164:167], v245 offset:50176
	ds_read_b128 v[168:171], v245 offset:51200
	ds_read_b128 v[172:175], v245 offset:52224
	ds_read_b128 v[176:179], v245 offset:53248
	ds_read_b128 v[180:183], v245 offset:54272
	ds_read_b128 v[184:187], v245 offset:55296
	ds_read_b128 v[188:191], v245 offset:56320
	global_load_lds_dwordx4 v218, s[48:49] offset:128
	s_add_i32 m0, s10, 0x1f80
	s_add_u32 s10, s48, 0xb0080
	s_addc_u32 s11, s49, 0
	s_add_i32 s18, s19, s95
	global_load_lds_dwordx4 v222, s[48:49] offset:128
	s_mov_b32 m0, s18
	s_nop 0
	global_load_lds_dwordx4 v218, s[10:11]
	s_add_i32 m0, s18, 0x2000
	s_nop 0
	global_load_lds_dwordx4 v222, s[10:11]
	s_add_i32 m0, s17, 0xffffff80
	s_nop 0
	global_load_lds_dwordx4 v216, s[50:51] offset:128
	s_add_i32 m0, s23, 0xffffff80
	s_nop 0
	global_load_lds_dwordx4 v220, s[50:51] offset:128
	s_waitcnt vmcnt(8)
	s_waitcnt lgkmcnt(0)
	s_barrier
	s_setprio 1
	s_waitcnt lgkmcnt(0)
	v_mfma_f32_16x16x32_bf16 v[60:63], v[64:67], v[160:163], v[60:63]
	v_mfma_f32_16x16x32_bf16 v[52:55], v[136:139], v[160:163], v[52:55]
	v_mfma_f32_16x16x32_bf16 v[44:47], v[64:67], v[168:171], v[44:47]
	v_mfma_f32_16x16x32_bf16 v[36:39], v[136:139], v[168:171], v[36:39]
	v_mfma_f32_16x16x32_bf16 v[28:31], v[64:67], v[176:179], v[28:31]
	v_mfma_f32_16x16x32_bf16 v[20:23], v[136:139], v[176:179], v[20:23]
	v_mfma_f32_16x16x32_bf16 v[12:15], v[64:67], v[184:187], v[12:15]
	v_mfma_f32_16x16x32_bf16 v[4:7], v[136:139], v[184:187], v[4:7]
	v_mfma_f32_16x16x32_bf16 v[60:63], v[68:71], v[164:167], v[60:63]
	v_mfma_f32_16x16x32_bf16 v[52:55], v[140:143], v[164:167], v[52:55]
	v_mfma_f32_16x16x32_bf16 v[44:47], v[68:71], v[172:175], v[44:47]
	v_mfma_f32_16x16x32_bf16 v[36:39], v[140:143], v[172:175], v[36:39]
	v_mfma_f32_16x16x32_bf16 v[28:31], v[68:71], v[180:183], v[28:31]
	v_mfma_f32_16x16x32_bf16 v[20:23], v[140:143], v[180:183], v[20:23]
	v_mfma_f32_16x16x32_bf16 v[12:15], v[68:71], v[188:191], v[12:15]
	v_mfma_f32_16x16x32_bf16 v[4:7], v[140:143], v[188:191], v[4:7]
	s_setprio 0
	s_setprio 1
	v_mfma_f32_16x16x32_bf16 v[56:59], v[144:147], v[160:163], v[56:59]
	v_mfma_f32_16x16x32_bf16 v[48:51], v[152:155], v[160:163], v[48:51]
	v_mfma_f32_16x16x32_bf16 v[40:43], v[144:147], v[168:171], v[40:43]
	v_mfma_f32_16x16x32_bf16 v[32:35], v[152:155], v[168:171], v[32:35]
	v_mfma_f32_16x16x32_bf16 v[24:27], v[144:147], v[176:179], v[24:27]
	v_mfma_f32_16x16x32_bf16 v[16:19], v[152:155], v[176:179], v[16:19]
	v_mfma_f32_16x16x32_bf16 v[8:11], v[144:147], v[184:187], v[8:11]
	v_mfma_f32_16x16x32_bf16 v[0:3], v[152:155], v[184:187], v[0:3]
	v_mfma_f32_16x16x32_bf16 v[56:59], v[148:151], v[164:167], v[56:59]
	v_mfma_f32_16x16x32_bf16 v[48:51], v[156:159], v[164:167], v[48:51]
	v_mfma_f32_16x16x32_bf16 v[40:43], v[148:151], v[172:175], v[40:43]
	v_mfma_f32_16x16x32_bf16 v[32:35], v[156:159], v[172:175], v[32:35]
	v_mfma_f32_16x16x32_bf16 v[24:27], v[148:151], v[180:183], v[24:27]
	v_mfma_f32_16x16x32_bf16 v[16:19], v[156:159], v[180:183], v[16:19]
	v_mfma_f32_16x16x32_bf16 v[8:11], v[148:151], v[188:191], v[8:11]
	v_mfma_f32_16x16x32_bf16 v[0:3], v[156:159], v[188:191], v[0:3]
	s_setprio 0
	s_barrier
	s_add_i32 s59, s59, 2
	s_add_u32 s57, s57, 0x100
	s_addc_u32 s58, s58, 0
	s_cmp_gt_u32 s59, 41
	s_mov_b64 s[10:11], s[8:9]
	s_cbranch_scc0 .LBB0_1024
	s_and_b64 vcc, exec, s[66:67]
	s_cbranch_vccz .LBB0_1027
	s_barrier
